# v65 + counted lgkmcnt waits: the first four MFMAs of an inproj1 k-step start as their own fragments land (11/10/9/8) instead of after all eight
# baseline (speedup 1.0000x reference)
.LBB0_569:
	s_add_i32 s5, s1, 0x8000
	s_and_b32 s13, s5, 0x8000
	s_add_u32 s13, s13, s38
	s_and_b32 s1, s1, 0x8000
	s_add_i32 s1, s1, 0
	v_add_u32_e32 v81, s1, v75
	v_add_u32_e32 v94, v81, v76
	v_add_u32_e32 v81, v81, v77
	s_add_u32 m0, s13, 0
	ds_read_b128 v[82:85], v94
	global_load_lds_dwordx4 v242, s[34:35]
	ds_read_b128 v[86:89], v94 offset:2048
	s_add_u32 m0, s13, 4096
	ds_read_b128 v[90:93], v94 offset:4096
	global_load_lds_dwordx4 v243, s[34:35]
	ds_read_b128 v[100:103], v94 offset:6144
	s_add_u32 m0, s13, 8192
	ds_read_b128 v[104:107], v81 offset:16384
	global_load_lds_dwordx4 v244, s[34:35]
	ds_read_b128 v[108:111], v81 offset:18432
	s_add_u32 m0, s13, 12288
	ds_read_b128 v[112:115], v81 offset:20480
	global_load_lds_dwordx4 v245, s[34:35]
	ds_read_b128 v[116:119], v81 offset:22528
	v_add_u32_e32 v206, s1, v78
	v_add_u32_e32 v207, v206, v76
	v_add_u32_e32 v208, v206, v77
	s_add_u32 m0, s13, 16384
	ds_read_b128 v[210:213], v207
	global_load_lds_dwordx4 v242, s[36:37]
	ds_read_b128 v[214:217], v207 offset:2048
	s_add_u32 m0, s13, 20480
	ds_read_b128 v[218:221], v207 offset:4096
	global_load_lds_dwordx4 v243, s[36:37]
	ds_read_b128 v[222:225], v207 offset:6144
	s_add_u32 m0, s13, 24576
	ds_read_b128 v[226:229], v208 offset:16384
	global_load_lds_dwordx4 v244, s[36:37]
	ds_read_b128 v[230:233], v208 offset:18432
	s_add_u32 m0, s13, 28672
	ds_read_b128 v[234:237], v208 offset:20480
	global_load_lds_dwordx4 v245, s[36:37]
	ds_read_b128 v[238:241], v208 offset:22528
	s_add_u32 s34, s34, 0x80
	s_addc_u32 s35, s35, 0
	s_add_u32 s36, s36, 0x80
	s_addc_u32 s37, s37, 0
	s_setprio 1
	s_waitcnt lgkmcnt(11)
	v_mfma_f32_16x16x32_bf16 v[60:63], v[104:107], v[82:85], v[60:63]
	s_waitcnt lgkmcnt(10)
	v_mfma_f32_16x16x32_bf16 v[56:59], v[108:111], v[82:85], v[56:59]
	s_waitcnt lgkmcnt(9)
	v_mfma_f32_16x16x32_bf16 v[52:55], v[112:115], v[82:85], v[52:55]
	s_waitcnt lgkmcnt(8)
	v_mfma_f32_16x16x32_bf16 v[48:51], v[116:119], v[82:85], v[48:51]
	v_mfma_f32_16x16x32_bf16 v[44:47], v[104:107], v[86:89], v[44:47]
	v_mfma_f32_16x16x32_bf16 v[40:43], v[108:111], v[86:89], v[40:43]
	v_mfma_f32_16x16x32_bf16 v[36:39], v[112:115], v[86:89], v[36:39]
	v_mfma_f32_16x16x32_bf16 v[32:35], v[116:119], v[86:89], v[32:35]
	v_mfma_f32_16x16x32_bf16 v[28:31], v[104:107], v[90:93], v[28:31]
	v_mfma_f32_16x16x32_bf16 v[24:27], v[108:111], v[90:93], v[24:27]
	v_mfma_f32_16x16x32_bf16 v[20:23], v[112:115], v[90:93], v[20:23]
	v_mfma_f32_16x16x32_bf16 v[16:19], v[116:119], v[90:93], v[16:19]
	v_mfma_f32_16x16x32_bf16 v[12:15], v[104:107], v[100:103], v[12:15]
	v_mfma_f32_16x16x32_bf16 v[8:11], v[108:111], v[100:103], v[8:11]
	v_mfma_f32_16x16x32_bf16 v[4:7], v[112:115], v[100:103], v[4:7]
	v_mfma_f32_16x16x32_bf16 v[0:3], v[116:119], v[100:103], v[0:3]
	s_waitcnt lgkmcnt(0)
	v_mfma_f32_16x16x32_bf16 v[60:63], v[226:229], v[210:213], v[60:63]
	v_mfma_f32_16x16x32_bf16 v[56:59], v[230:233], v[210:213], v[56:59]
	v_mfma_f32_16x16x32_bf16 v[52:55], v[234:237], v[210:213], v[52:55]
	v_mfma_f32_16x16x32_bf16 v[48:51], v[238:241], v[210:213], v[48:51]
	v_mfma_f32_16x16x32_bf16 v[44:47], v[226:229], v[214:217], v[44:47]
	v_mfma_f32_16x16x32_bf16 v[40:43], v[230:233], v[214:217], v[40:43]
	v_mfma_f32_16x16x32_bf16 v[36:39], v[234:237], v[214:217], v[36:39]
	v_mfma_f32_16x16x32_bf16 v[32:35], v[238:241], v[214:217], v[32:35]
	v_mfma_f32_16x16x32_bf16 v[28:31], v[226:229], v[218:221], v[28:31]
	v_mfma_f32_16x16x32_bf16 v[24:27], v[230:233], v[218:221], v[24:27]
	v_mfma_f32_16x16x32_bf16 v[20:23], v[234:237], v[218:221], v[20:23]
	v_mfma_f32_16x16x32_bf16 v[16:19], v[238:241], v[218:221], v[16:19]
	v_mfma_f32_16x16x32_bf16 v[12:15], v[226:229], v[222:225], v[12:15]
	v_mfma_f32_16x16x32_bf16 v[8:11], v[230:233], v[222:225], v[8:11]
	v_mfma_f32_16x16x32_bf16 v[4:7], v[234:237], v[222:225], v[4:7]
	v_mfma_f32_16x16x32_bf16 v[0:3], v[238:241], v[222:225], v[0:3]
	s_setprio 0
	s_waitcnt vmcnt(0)
	s_add_u32 s6, s6, 0x80
	s_addc_u32 s7, s7, 0
	s_cmpk_lg_i32 s6, 0x780
	s_mov_b32 s1, s5
	s_waitcnt vmcnt(0)
	s_barrier
	s_cbranch_scc1 .LBB0_569
	v_add_u32_e32 v81, v79, v77
	ds_read_b128 v[70:73], v81 offset:55296
	ds_read_b128 v[82:85], v81 offset:53248
	ds_read_b128 v[86:89], v81 offset:51200
	ds_read_b128 v[90:93], v81 offset:49152
	v_add_u32_e32 v81, v79, v76
	ds_read_b128 v[100:103], v81 offset:38912
	ds_read_b128 v[104:107], v81 offset:36864
	ds_read_b128 v[108:111], v81 offset:34816
	ds_read_b128 v[112:115], v81 offset:32768
	s_setprio 1
	s_waitcnt lgkmcnt(0)
	v_mfma_f32_16x16x32_bf16 v[60:63], v[90:93], v[112:115], v[60:63]
	v_mfma_f32_16x16x32_bf16 v[56:59], v[86:89], v[112:115], v[56:59]
	v_mfma_f32_16x16x32_bf16 v[52:55], v[82:85], v[112:115], v[52:55]
	v_mfma_f32_16x16x32_bf16 v[48:51], v[70:73], v[112:115], v[48:51]
	v_mfma_f32_16x16x32_bf16 v[44:47], v[90:93], v[108:111], v[44:47]
	v_mfma_f32_16x16x32_bf16 v[40:43], v[86:89], v[108:111], v[40:43]
	v_mfma_f32_16x16x32_bf16 v[36:39], v[82:85], v[108:111], v[36:39]
	v_mfma_f32_16x16x32_bf16 v[32:35], v[70:73], v[108:111], v[32:35]
	v_mfma_f32_16x16x32_bf16 v[28:31], v[90:93], v[104:107], v[28:31]
	v_mfma_f32_16x16x32_bf16 v[24:27], v[86:89], v[104:107], v[24:27]
	v_mfma_f32_16x16x32_bf16 v[20:23], v[82:85], v[104:107], v[20:23]
	v_mfma_f32_16x16x32_bf16 v[16:19], v[70:73], v[104:107], v[16:19]
	v_mfma_f32_16x16x32_bf16 v[12:15], v[90:93], v[100:103], v[12:15]
	v_mfma_f32_16x16x32_bf16 v[8:11], v[86:89], v[100:103], v[8:11]
	v_mfma_f32_16x16x32_bf16 v[4:7], v[82:85], v[100:103], v[4:7]
	v_mfma_f32_16x16x32_bf16 v[0:3], v[70:73], v[100:103], v[0:3]
	s_setprio 0
	v_add_u32_e32 v81, v80, v76
	ds_read_b128 v[70:73], v81 offset:32768
	ds_read_b128 v[82:85], v81 offset:34816
	ds_read_b128 v[86:89], v81 offset:36864
	ds_read_b128 v[90:93], v81 offset:38912
	v_add_u32_e32 v81, v80, v77
	ds_read_b128 v[100:103], v81 offset:49152
	ds_read_b128 v[104:107], v81 offset:51200
	ds_read_b128 v[108:111], v81 offset:53248
	ds_read_b128 v[112:115], v81 offset:55296
	s_setprio 1
	s_waitcnt lgkmcnt(3)
	v_mfma_f32_16x16x32_bf16 v[60:63], v[100:103], v[70:73], v[60:63]
	s_waitcnt lgkmcnt(2)
	v_mfma_f32_16x16x32_bf16 v[56:59], v[104:107], v[70:73], v[56:59]
	s_waitcnt lgkmcnt(1)
	v_mfma_f32_16x16x32_bf16 v[52:55], v[108:111], v[70:73], v[52:55]
	s_waitcnt lgkmcnt(0)
	v_mfma_f32_16x16x32_bf16 v[48:51], v[112:115], v[70:73], v[48:51]
	v_mfma_f32_16x16x32_bf16 v[44:47], v[100:103], v[82:85], v[44:47]
	v_mfma_f32_16x16x32_bf16 v[40:43], v[104:107], v[82:85], v[40:43]
	v_mfma_f32_16x16x32_bf16 v[36:39], v[108:111], v[82:85], v[36:39]
	v_mfma_f32_16x16x32_bf16 v[32:35], v[112:115], v[82:85], v[32:35]
	v_mfma_f32_16x16x32_bf16 v[28:31], v[100:103], v[86:89], v[28:31]
	v_mfma_f32_16x16x32_bf16 v[24:27], v[104:107], v[86:89], v[24:27]
	v_mfma_f32_16x16x32_bf16 v[20:23], v[108:111], v[86:89], v[20:23]
	v_mfma_f32_16x16x32_bf16 v[16:19], v[112:115], v[86:89], v[16:19]
	v_mfma_f32_16x16x32_bf16 v[12:15], v[100:103], v[90:93], v[12:15]
	v_mfma_f32_16x16x32_bf16 v[8:11], v[104:107], v[90:93], v[8:11]
	v_mfma_f32_16x16x32_bf16 v[4:7], v[108:111], v[90:93], v[4:7]
	v_mfma_f32_16x16x32_bf16 v[0:3], v[112:115], v[90:93], v[0:3]
	s_setprio 0
	v_mov_b32_e32 v70, v97
	s_waitcnt vmcnt(0)
	s_barrier
	s_lshl_b32 s0, s0, 7
	v_add_u32_e32 v70, v70, v176
	v_and_b32_e32 v71, 64, v70
	v_ashrrev_i32_e32 v72, 1, v70
	v_lshrrev_b32_e32 v73, 2, v70
	v_and_or_b32 v70, v70, 15, s0
	s_lshl_b32 s0, s4, 7
	s_ashr_i32 s1, s0, 31
	s_lshl_b64 s[0:1], s[0:1], 1
	s_mov_b32 s6, 0
	v_and_b32_e32 v72, 0xffffffc0, v72
	s_add_u32 s0, s2, s0
	v_and_or_b32 v81, v73, 12, v71
	v_add_u32_e32 v82, v70, v72
	s_addc_u32 s1, s8, s1
	v_lshlrev_b32_e32 v96, 1, v81
	v_and_b32_sdwa v81, v62, v154 dst_sel:DWORD dst_unused:UNUSED_PAD src0_sel:WORD_1 src1_sel:DWORD
	v_and_b32_sdwa v83, v60, v154 dst_sel:DWORD dst_unused:UNUSED_PAD src0_sel:WORD_1 src1_sel:DWORD
	v_add3_u32 v60, v60, v83, s33
	v_add3_u32 v62, v62, v81, s33
	v_and_b32_sdwa v81, v63, v154 dst_sel:DWORD dst_unused:UNUSED_PAD src0_sel:WORD_1 src1_sel:DWORD
	v_and_b32_sdwa v83, v61, v154 dst_sel:DWORD dst_unused:UNUSED_PAD src0_sel:WORD_1 src1_sel:DWORD
	v_mov_b64_e32 v[70:71], s[0:1]
	s_movk_i32 s4, 0x3200
	v_add3_u32 v63, v63, v81, s33
	v_add3_u32 v61, v61, v83, s33
	v_mad_i64_i32 v[72:73], s[0:1], v82, s4, v[70:71]
	v_and_b32_e32 v63, 0xffff0000, v63
	v_and_b32_e32 v81, 0xffff0000, v61
	v_lshl_add_u64 v[72:73], v[72:73], 0, v[96:97]
	v_or_b32_sdwa v61, v63, v62 dst_sel:DWORD dst_unused:UNUSED_PAD src0_sel:DWORD src1_sel:WORD_1
	v_or_b32_sdwa v60, v81, v60 dst_sel:DWORD dst_unused:UNUSED_PAD src0_sel:DWORD src1_sel:WORD_1
	global_store_dwordx2 v[72:73], v[60:61], off
	v_and_b32_sdwa v60, v58, v154 dst_sel:DWORD dst_unused:UNUSED_PAD src0_sel:WORD_1 src1_sel:DWORD
	v_and_b32_sdwa v61, v56, v154 dst_sel:DWORD dst_unused:UNUSED_PAD src0_sel:WORD_1 src1_sel:DWORD
	v_add3_u32 v56, v56, v61, s33
	v_add3_u32 v58, v58, v60, s33
	v_and_b32_sdwa v60, v59, v154 dst_sel:DWORD dst_unused:UNUSED_PAD src0_sel:WORD_1 src1_sel:DWORD
	v_and_b32_sdwa v61, v57, v154 dst_sel:DWORD dst_unused:UNUSED_PAD src0_sel:WORD_1 src1_sel:DWORD
	v_add3_u32 v59, v59, v60, s33
	v_add3_u32 v57, v57, v61, s33
	v_and_b32_e32 v59, 0xffff0000, v59
	v_and_b32_e32 v60, 0xffff0000, v57
	v_or_b32_sdwa v57, v59, v58 dst_sel:DWORD dst_unused:UNUSED_PAD src0_sel:DWORD src1_sel:WORD_1
	v_or_b32_sdwa v56, v60, v56 dst_sel:DWORD dst_unused:UNUSED_PAD src0_sel:DWORD src1_sel:WORD_1
	global_store_dwordx2 v[72:73], v[56:57], off offset:32
	v_and_b32_sdwa v56, v54, v154 dst_sel:DWORD dst_unused:UNUSED_PAD src0_sel:WORD_1 src1_sel:DWORD
	v_and_b32_sdwa v57, v52, v154 dst_sel:DWORD dst_unused:UNUSED_PAD src0_sel:WORD_1 src1_sel:DWORD
	v_add3_u32 v52, v52, v57, s33
	v_add3_u32 v54, v54, v56, s33
	v_and_b32_sdwa v56, v55, v154 dst_sel:DWORD dst_unused:UNUSED_PAD src0_sel:WORD_1 src1_sel:DWORD
	v_and_b32_sdwa v57, v53, v154 dst_sel:DWORD dst_unused:UNUSED_PAD src0_sel:WORD_1 src1_sel:DWORD
	v_add3_u32 v55, v55, v56, s33
	v_add3_u32 v53, v53, v57, s33
	v_and_b32_e32 v55, 0xffff0000, v55
	v_and_b32_e32 v56, 0xffff0000, v53
	v_or_b32_sdwa v53, v55, v54 dst_sel:DWORD dst_unused:UNUSED_PAD src0_sel:DWORD src1_sel:WORD_1
	v_or_b32_sdwa v52, v56, v52 dst_sel:DWORD dst_unused:UNUSED_PAD src0_sel:DWORD src1_sel:WORD_1
	global_store_dwordx2 v[72:73], v[52:53], off offset:64
	v_and_b32_sdwa v52, v50, v154 dst_sel:DWORD dst_unused:UNUSED_PAD src0_sel:WORD_1 src1_sel:DWORD
	v_and_b32_sdwa v53, v48, v154 dst_sel:DWORD dst_unused:UNUSED_PAD src0_sel:WORD_1 src1_sel:DWORD
	v_add3_u32 v48, v48, v53, s33
	v_add3_u32 v50, v50, v52, s33
	v_and_b32_sdwa v52, v51, v154 dst_sel:DWORD dst_unused:UNUSED_PAD src0_sel:WORD_1 src1_sel:DWORD
	v_and_b32_sdwa v53, v49, v154 dst_sel:DWORD dst_unused:UNUSED_PAD src0_sel:WORD_1 src1_sel:DWORD
	v_add3_u32 v51, v51, v52, s33
	v_add3_u32 v49, v49, v53, s33
	v_and_b32_e32 v51, 0xffff0000, v51
	v_and_b32_e32 v52, 0xffff0000, v49
	v_or_b32_sdwa v49, v51, v50 dst_sel:DWORD dst_unused:UNUSED_PAD src0_sel:DWORD src1_sel:WORD_1
	v_or_b32_sdwa v48, v52, v48 dst_sel:DWORD dst_unused:UNUSED_PAD src0_sel:DWORD src1_sel:WORD_1
	global_store_dwordx2 v[72:73], v[48:49], off offset:96
	v_and_b32_sdwa v50, v46, v154 dst_sel:DWORD dst_unused:UNUSED_PAD src0_sel:WORD_1 src1_sel:DWORD
	v_and_b32_sdwa v51, v44, v154 dst_sel:DWORD dst_unused:UNUSED_PAD src0_sel:WORD_1 src1_sel:DWORD
	v_add3_u32 v44, v44, v51, s33
	v_add3_u32 v46, v46, v50, s33
	v_and_b32_sdwa v50, v47, v154 dst_sel:DWORD dst_unused:UNUSED_PAD src0_sel:WORD_1 src1_sel:DWORD
	v_and_b32_sdwa v51, v45, v154 dst_sel:DWORD dst_unused:UNUSED_PAD src0_sel:WORD_1 src1_sel:DWORD
	v_or_b32_e32 v48, 16, v82
	v_add3_u32 v47, v47, v50, s33
	v_add3_u32 v45, v45, v51, s33
	v_mad_i64_i32 v[48:49], s[0:1], v48, s4, v[70:71]
	v_and_b32_e32 v47, 0xffff0000, v47
	v_and_b32_e32 v50, 0xffff0000, v45
	v_lshl_add_u64 v[48:49], v[48:49], 0, v[96:97]
	v_or_b32_sdwa v45, v47, v46 dst_sel:DWORD dst_unused:UNUSED_PAD src0_sel:DWORD src1_sel:WORD_1
	v_or_b32_sdwa v44, v50, v44 dst_sel:DWORD dst_unused:UNUSED_PAD src0_sel:DWORD src1_sel:WORD_1
	global_store_dwordx2 v[48:49], v[44:45], off
	v_and_b32_sdwa v44, v42, v154 dst_sel:DWORD dst_unused:UNUSED_PAD src0_sel:WORD_1 src1_sel:DWORD
	v_and_b32_sdwa v45, v40, v154 dst_sel:DWORD dst_unused:UNUSED_PAD src0_sel:WORD_1 src1_sel:DWORD
	v_add3_u32 v40, v40, v45, s33
	v_add3_u32 v42, v42, v44, s33
	v_and_b32_sdwa v44, v43, v154 dst_sel:DWORD dst_unused:UNUSED_PAD src0_sel:WORD_1 src1_sel:DWORD
	v_and_b32_sdwa v45, v41, v154 dst_sel:DWORD dst_unused:UNUSED_PAD src0_sel:WORD_1 src1_sel:DWORD
	v_add3_u32 v43, v43, v44, s33
	v_add3_u32 v41, v41, v45, s33
	v_and_b32_e32 v43, 0xffff0000, v43
	v_and_b32_e32 v44, 0xffff0000, v41
	v_or_b32_sdwa v41, v43, v42 dst_sel:DWORD dst_unused:UNUSED_PAD src0_sel:DWORD src1_sel:WORD_1
	v_or_b32_sdwa v40, v44, v40 dst_sel:DWORD dst_unused:UNUSED_PAD src0_sel:DWORD src1_sel:WORD_1
	global_store_dwordx2 v[48:49], v[40:41], off offset:32
	v_and_b32_sdwa v40, v38, v154 dst_sel:DWORD dst_unused:UNUSED_PAD src0_sel:WORD_1 src1_sel:DWORD
	v_and_b32_sdwa v41, v36, v154 dst_sel:DWORD dst_unused:UNUSED_PAD src0_sel:WORD_1 src1_sel:DWORD
	v_add3_u32 v36, v36, v41, s33
	v_add3_u32 v38, v38, v40, s33
	v_and_b32_sdwa v40, v39, v154 dst_sel:DWORD dst_unused:UNUSED_PAD src0_sel:WORD_1 src1_sel:DWORD
	v_and_b32_sdwa v41, v37, v154 dst_sel:DWORD dst_unused:UNUSED_PAD src0_sel:WORD_1 src1_sel:DWORD
	v_add3_u32 v39, v39, v40, s33
	v_add3_u32 v37, v37, v41, s33
	v_and_b32_e32 v39, 0xffff0000, v39
	v_and_b32_e32 v40, 0xffff0000, v37
	v_or_b32_sdwa v37, v39, v38 dst_sel:DWORD dst_unused:UNUSED_PAD src0_sel:DWORD src1_sel:WORD_1
	v_or_b32_sdwa v36, v40, v36 dst_sel:DWORD dst_unused:UNUSED_PAD src0_sel:DWORD src1_sel:WORD_1
	global_store_dwordx2 v[48:49], v[36:37], off offset:64
	v_and_b32_sdwa v36, v34, v154 dst_sel:DWORD dst_unused:UNUSED_PAD src0_sel:WORD_1 src1_sel:DWORD
	v_and_b32_sdwa v37, v32, v154 dst_sel:DWORD dst_unused:UNUSED_PAD src0_sel:WORD_1 src1_sel:DWORD
	v_add3_u32 v32, v32, v37, s33
	v_add3_u32 v34, v34, v36, s33
	v_and_b32_sdwa v36, v35, v154 dst_sel:DWORD dst_unused:UNUSED_PAD src0_sel:WORD_1 src1_sel:DWORD
	v_and_b32_sdwa v37, v33, v154 dst_sel:DWORD dst_unused:UNUSED_PAD src0_sel:WORD_1 src1_sel:DWORD
	v_add3_u32 v35, v35, v36, s33
	v_add3_u32 v33, v33, v37, s33
	v_and_b32_e32 v35, 0xffff0000, v35
	v_and_b32_e32 v36, 0xffff0000, v33
	v_or_b32_sdwa v33, v35, v34 dst_sel:DWORD dst_unused:UNUSED_PAD src0_sel:DWORD src1_sel:WORD_1
	v_or_b32_sdwa v32, v36, v32 dst_sel:DWORD dst_unused:UNUSED_PAD src0_sel:DWORD src1_sel:WORD_1
	global_store_dwordx2 v[48:49], v[32:33], off offset:96
	v_and_b32_sdwa v34, v30, v154 dst_sel:DWORD dst_unused:UNUSED_PAD src0_sel:WORD_1 src1_sel:DWORD
	v_and_b32_sdwa v35, v28, v154 dst_sel:DWORD dst_unused:UNUSED_PAD src0_sel:WORD_1 src1_sel:DWORD
	v_add3_u32 v28, v28, v35, s33
	v_add3_u32 v30, v30, v34, s33
	v_and_b32_sdwa v34, v31, v154 dst_sel:DWORD dst_unused:UNUSED_PAD src0_sel:WORD_1 src1_sel:DWORD
	v_and_b32_sdwa v35, v29, v154 dst_sel:DWORD dst_unused:UNUSED_PAD src0_sel:WORD_1 src1_sel:DWORD
	v_or_b32_e32 v32, 32, v82
	v_add3_u32 v31, v31, v34, s33
	v_add3_u32 v29, v29, v35, s33
	v_mad_i64_i32 v[32:33], s[0:1], v32, s4, v[70:71]
	v_and_b32_e32 v31, 0xffff0000, v31
	v_and_b32_e32 v34, 0xffff0000, v29
	v_lshl_add_u64 v[32:33], v[32:33], 0, v[96:97]
	v_or_b32_sdwa v29, v31, v30 dst_sel:DWORD dst_unused:UNUSED_PAD src0_sel:DWORD src1_sel:WORD_1
	v_or_b32_sdwa v28, v34, v28 dst_sel:DWORD dst_unused:UNUSED_PAD src0_sel:DWORD src1_sel:WORD_1
	global_store_dwordx2 v[32:33], v[28:29], off
	v_and_b32_sdwa v28, v26, v154 dst_sel:DWORD dst_unused:UNUSED_PAD src0_sel:WORD_1 src1_sel:DWORD
	v_and_b32_sdwa v29, v24, v154 dst_sel:DWORD dst_unused:UNUSED_PAD src0_sel:WORD_1 src1_sel:DWORD
	v_add3_u32 v24, v24, v29, s33
	v_add3_u32 v26, v26, v28, s33
	v_and_b32_sdwa v28, v27, v154 dst_sel:DWORD dst_unused:UNUSED_PAD src0_sel:WORD_1 src1_sel:DWORD
	v_and_b32_sdwa v29, v25, v154 dst_sel:DWORD dst_unused:UNUSED_PAD src0_sel:WORD_1 src1_sel:DWORD
	v_add3_u32 v27, v27, v28, s33
	v_add3_u32 v25, v25, v29, s33
	v_and_b32_e32 v27, 0xffff0000, v27
	v_and_b32_e32 v28, 0xffff0000, v25
	v_or_b32_sdwa v25, v27, v26 dst_sel:DWORD dst_unused:UNUSED_PAD src0_sel:DWORD src1_sel:WORD_1
	v_or_b32_sdwa v24, v28, v24 dst_sel:DWORD dst_unused:UNUSED_PAD src0_sel:DWORD src1_sel:WORD_1
	global_store_dwordx2 v[32:33], v[24:25], off offset:32
	v_and_b32_sdwa v24, v22, v154 dst_sel:DWORD dst_unused:UNUSED_PAD src0_sel:WORD_1 src1_sel:DWORD
	v_and_b32_sdwa v25, v20, v154 dst_sel:DWORD dst_unused:UNUSED_PAD src0_sel:WORD_1 src1_sel:DWORD
	v_add3_u32 v20, v20, v25, s33
	v_add3_u32 v22, v22, v24, s33
	v_and_b32_sdwa v24, v23, v154 dst_sel:DWORD dst_unused:UNUSED_PAD src0_sel:WORD_1 src1_sel:DWORD
	v_and_b32_sdwa v25, v21, v154 dst_sel:DWORD dst_unused:UNUSED_PAD src0_sel:WORD_1 src1_sel:DWORD
	v_add3_u32 v23, v23, v24, s33
	v_add3_u32 v21, v21, v25, s33
	v_and_b32_e32 v23, 0xffff0000, v23
	v_and_b32_e32 v24, 0xffff0000, v21
	v_or_b32_sdwa v21, v23, v22 dst_sel:DWORD dst_unused:UNUSED_PAD src0_sel:DWORD src1_sel:WORD_1
	v_or_b32_sdwa v20, v24, v20 dst_sel:DWORD dst_unused:UNUSED_PAD src0_sel:DWORD src1_sel:WORD_1
	global_store_dwordx2 v[32:33], v[20:21], off offset:64
	v_and_b32_sdwa v20, v18, v154 dst_sel:DWORD dst_unused:UNUSED_PAD src0_sel:WORD_1 src1_sel:DWORD
	v_and_b32_sdwa v21, v16, v154 dst_sel:DWORD dst_unused:UNUSED_PAD src0_sel:WORD_1 src1_sel:DWORD
	v_add3_u32 v16, v16, v21, s33
	v_add3_u32 v18, v18, v20, s33
	v_and_b32_sdwa v20, v19, v154 dst_sel:DWORD dst_unused:UNUSED_PAD src0_sel:WORD_1 src1_sel:DWORD
	v_and_b32_sdwa v21, v17, v154 dst_sel:DWORD dst_unused:UNUSED_PAD src0_sel:WORD_1 src1_sel:DWORD
	v_add3_u32 v19, v19, v20, s33
	v_add3_u32 v17, v17, v21, s33
	v_and_b32_e32 v19, 0xffff0000, v19
	v_and_b32_e32 v20, 0xffff0000, v17
	v_or_b32_sdwa v17, v19, v18 dst_sel:DWORD dst_unused:UNUSED_PAD src0_sel:DWORD src1_sel:WORD_1
	v_or_b32_sdwa v16, v20, v16 dst_sel:DWORD dst_unused:UNUSED_PAD src0_sel:DWORD src1_sel:WORD_1
	global_store_dwordx2 v[32:33], v[16:17], off offset:96
	v_and_b32_sdwa v18, v14, v154 dst_sel:DWORD dst_unused:UNUSED_PAD src0_sel:WORD_1 src1_sel:DWORD
	v_and_b32_sdwa v19, v12, v154 dst_sel:DWORD dst_unused:UNUSED_PAD src0_sel:WORD_1 src1_sel:DWORD
	v_add3_u32 v12, v12, v19, s33
	v_add3_u32 v14, v14, v18, s33
	v_and_b32_sdwa v18, v15, v154 dst_sel:DWORD dst_unused:UNUSED_PAD src0_sel:WORD_1 src1_sel:DWORD
	v_and_b32_sdwa v19, v13, v154 dst_sel:DWORD dst_unused:UNUSED_PAD src0_sel:WORD_1 src1_sel:DWORD
	v_or_b32_e32 v16, 48, v82
	v_add3_u32 v15, v15, v18, s33
	v_add3_u32 v13, v13, v19, s33
	v_mad_i64_i32 v[16:17], s[0:1], v16, s4, v[70:71]
	v_and_b32_e32 v15, 0xffff0000, v15
	v_and_b32_e32 v18, 0xffff0000, v13
	v_lshl_add_u64 v[16:17], v[16:17], 0, v[96:97]
	v_or_b32_sdwa v13, v15, v14 dst_sel:DWORD dst_unused:UNUSED_PAD src0_sel:DWORD src1_sel:WORD_1
	v_or_b32_sdwa v12, v18, v12 dst_sel:DWORD dst_unused:UNUSED_PAD src0_sel:DWORD src1_sel:WORD_1
	global_store_dwordx2 v[16:17], v[12:13], off
	v_and_b32_sdwa v12, v10, v154 dst_sel:DWORD dst_unused:UNUSED_PAD src0_sel:WORD_1 src1_sel:DWORD
	v_and_b32_sdwa v13, v8, v154 dst_sel:DWORD dst_unused:UNUSED_PAD src0_sel:WORD_1 src1_sel:DWORD
	v_add3_u32 v8, v8, v13, s33
	v_add3_u32 v10, v10, v12, s33
	v_and_b32_sdwa v12, v11, v154 dst_sel:DWORD dst_unused:UNUSED_PAD src0_sel:WORD_1 src1_sel:DWORD
	v_and_b32_sdwa v13, v9, v154 dst_sel:DWORD dst_unused:UNUSED_PAD src0_sel:WORD_1 src1_sel:DWORD
	v_add3_u32 v11, v11, v12, s33
	v_add3_u32 v9, v9, v13, s33
	v_and_b32_e32 v11, 0xffff0000, v11
	v_and_b32_e32 v12, 0xffff0000, v9
	v_or_b32_sdwa v9, v11, v10 dst_sel:DWORD dst_unused:UNUSED_PAD src0_sel:DWORD src1_sel:WORD_1
	v_or_b32_sdwa v8, v12, v8 dst_sel:DWORD dst_unused:UNUSED_PAD src0_sel:DWORD src1_sel:WORD_1
	global_store_dwordx2 v[16:17], v[8:9], off offset:32
	v_and_b32_sdwa v8, v6, v154 dst_sel:DWORD dst_unused:UNUSED_PAD src0_sel:WORD_1 src1_sel:DWORD
	v_and_b32_sdwa v9, v4, v154 dst_sel:DWORD dst_unused:UNUSED_PAD src0_sel:WORD_1 src1_sel:DWORD
	v_add3_u32 v4, v4, v9, s33
	v_add3_u32 v6, v6, v8, s33
	v_and_b32_sdwa v8, v7, v154 dst_sel:DWORD dst_unused:UNUSED_PAD src0_sel:WORD_1 src1_sel:DWORD
	v_and_b32_sdwa v9, v5, v154 dst_sel:DWORD dst_unused:UNUSED_PAD src0_sel:WORD_1 src1_sel:DWORD
	v_add3_u32 v7, v7, v8, s33
	v_add3_u32 v5, v5, v9, s33
	v_and_b32_e32 v7, 0xffff0000, v7
	v_and_b32_e32 v8, 0xffff0000, v5
	v_or_b32_sdwa v5, v7, v6 dst_sel:DWORD dst_unused:UNUSED_PAD src0_sel:DWORD src1_sel:WORD_1
	v_or_b32_sdwa v4, v8, v4 dst_sel:DWORD dst_unused:UNUSED_PAD src0_sel:DWORD src1_sel:WORD_1
	global_store_dwordx2 v[16:17], v[4:5], off offset:64
	v_and_b32_sdwa v4, v2, v154 dst_sel:DWORD dst_unused:UNUSED_PAD src0_sel:WORD_1 src1_sel:DWORD
	v_and_b32_sdwa v5, v0, v154 dst_sel:DWORD dst_unused:UNUSED_PAD src0_sel:WORD_1 src1_sel:DWORD
	v_add3_u32 v0, v0, v5, s33
	v_add3_u32 v2, v2, v4, s33
	v_and_b32_sdwa v4, v3, v154 dst_sel:DWORD dst_unused:UNUSED_PAD src0_sel:WORD_1 src1_sel:DWORD
	v_and_b32_sdwa v5, v1, v154 dst_sel:DWORD dst_unused:UNUSED_PAD src0_sel:WORD_1 src1_sel:DWORD
	v_add3_u32 v3, v3, v4, s33
	v_add3_u32 v1, v1, v5, s33
	v_and_b32_e32 v3, 0xffff0000, v3
	v_and_b32_e32 v4, 0xffff0000, v1
	v_or_b32_sdwa v1, v3, v2 dst_sel:DWORD dst_unused:UNUSED_PAD src0_sel:DWORD src1_sel:WORD_1
	v_or_b32_sdwa v0, v4, v0 dst_sel:DWORD dst_unused:UNUSED_PAD src0_sel:DWORD src1_sel:WORD_1
	global_store_dwordx2 v[16:17], v[0:1], off offset:96
